# dense main loop ring-DMA in scalar-base form (tile base in SGPRs, constant per-lane 32-bit offsets): five 64-bit VALU adds per tile per wave removed
# speedup vs baseline: 1.0116x; 1.0011x over previous
; #define PP_BAR(VM) do { if (VM) { asm volatile("s_waitcnt vmcnt(4) lgkmcnt(0)\n\ts_barrier" ::: "memory"); } else { asm volatile("s_waitcnt vmcnt(0) lgkmcnt(0)\n\ts_barrier" ::: "memory"); } } while (0)
; #define PP_BAR_PLAIN() asm volatile("s_waitcnt lgkmcnt(0)\n\ts_barrier" ::: "memory")
;     ...
;   int krow[2], kcol[2], vrow[2], vcol[2];
; #pragma unroll
;   for (int i = 0; i < 2; ++i) { const int pc = 2 * wid + i;
;     krow[i] = pc * 4 + (lane >> 4); kcol[i] = (((lane & 15) ^ (krow[i] & 7)) << 3);
;     const int sub = pc * 2 + (lane >> 5), kk = ((sub >> 2) << 3) + ((lane & 31) >> 2);
;     vrow[i] = kk; vcol[i] = ((sub & 3) << 5) + ((lane & 3) << 3); }
;   unsigned kdo[2], vdo[2];
; #pragma unroll
;   for (int i = 0; i < 2; ++i) { kdo[i] = (unsigned)(krow[i] * (int)ks + kcol[i]); vdo[i] = (unsigned)(vrow[i] * (int)ks + vcol[i]); }
;     ...
;   } else if constexpr (MK_PP) {
;     const bool grpB = wid >= 4;
;     ...
;     m_reg = 0.f; f32x16 negm = f32x16{};
;     ...
;     if (grpB) PP_BAR_PLAIN();
;     qkt(pA0, pA1, KBUF(0), qr, r32, hi);
;     if (grpB) PP_BAR(2 < NT); else PP_BAR_PLAIN();
;     for (int t = 0; t < NT; ++t) {
;       if (grpB && t + 3 < NT) DMA(t + 3, (t + 3) & 3);
.LBB0_55:
	s_and_b32 s12, s12, 0x3fffffc0
	s_lshr_b32 s38, s25, 7
	v_and_b32_e32 v6, 63, v212
	s_lshl_b32 s12, s12, 2
	s_and_b32 s38, s38, 1
	s_add_i32 s12, s12, 0
	v_lshlrev_b32_e32 v8, 4, v6
	s_lshl_b32 s42, s38, 22
	s_add_i32 s12, s12, 0x20000
	v_lshlrev_b32_e32 v7, 3, v6
	v_and_b32_e32 v8, 0xc0, v8
	v_lshlrev_b32_e32 v9, 1, v6
	v_and_or_b32 v8, v7, 24, v8
	v_and_b32_e32 v9, 32, v9
	v_and_b32_e32 v7, 0x100, v7
	s_cmp_lg_u32 s88, -1
	v_or3_b32 v235, v8, v9, v7
	v_lshlrev_b32_e32 v7, 4, v212
	s_cselect_b32 s38, s88, 0
	s_add_u32 s42, s42, s40
	v_and_b32_e32 v7, 0x70, v7
	s_addc_u32 s43, 0, s41
	v_bitop3_b32 v239, v0, v2, v7 bitop3:0xde
	v_bitop3_b32 v238, v3, v2, v7 bitop3:0xde
	v_bitop3_b32 v237, v4, v2, v7 bitop3:0xde
	v_bitop3_b32 v236, v5, v2, v7 bitop3:0xde
	v_add_u32_e32 v2, s15, v243
	s_add_u32 s40, s94, s42
	v_add3_u32 v2, v2, v162, v242
	v_mov_b32_e32 v3, v1
	s_addc_u32 s41, s95, s43
	v_lshlrev_b32_e32 v208, 1, v2
	v_add_u32_e32 v209, 0x80, v208
	s_add_u32 s6, s40, 0xf00c000
	s_addc_u32 s7, s41, 0
	s_add_u32 s40, s9, s42
	v_add3_u32 v2, s15, v240, v241
	s_addc_u32 s41, s21, s43
	s_addk_i32 s15, 0x200
	v_lshlrev_b32_e32 v210, 1, v2
	s_mov_b64 s[4:5], s[40:41]
	v_add3_u32 v2, s15, v240, v213
	v_mov_b32_e32 v16, v1
	v_mov_b32_e32 v17, v1
	v_add_u32_e32 v244, s38, v235
	v_cmp_gt_u32_e64 s[38:39], 32, v6
	v_lshlrev_b32_e32 v211, 1, v2
	v_mov_b32_e32 v2, v1
	v_mov_b32_e32 v4, v1
	v_mov_b32_e32 v5, v1
	v_mov_b32_e32 v6, v1
	v_mov_b32_e32 v7, v1
	v_mov_b32_e32 v8, v1
	v_mov_b32_e32 v9, v1
	v_mov_b32_e32 v10, v1
	v_mov_b32_e32 v11, v1
	v_mov_b32_e32 v12, v1
	v_mov_b32_e32 v13, v1
	v_mov_b32_e32 v14, v1
	v_mov_b32_e32 v15, v1
	v_mov_b32_e32 v240, 0
	v_mov_b64_e32 v[64:65], v[16:17]
	v_mov_b64_e32 v[48:49], v[16:17]
	v_mov_b64_e32 v[32:33], v[16:17]
	v_lshl_add_u32 v234, v232, 2, s12
	s_mov_b64 s[86:87], 0
	v_mov_b64_e32 v[62:63], v[14:15]
	v_mov_b64_e32 v[60:61], v[12:13]
	v_mov_b64_e32 v[58:59], v[10:11]
	v_mov_b64_e32 v[56:57], v[8:9]
	v_mov_b64_e32 v[54:55], v[6:7]
	v_mov_b64_e32 v[52:53], v[4:5]
	v_mov_b64_e32 v[50:51], v[2:3]
	v_mov_b64_e32 v[46:47], v[14:15]
	v_mov_b64_e32 v[44:45], v[12:13]
	v_mov_b64_e32 v[42:43], v[10:11]
	v_mov_b64_e32 v[40:41], v[8:9]
	v_mov_b64_e32 v[38:39], v[6:7]
	v_mov_b64_e32 v[36:37], v[4:5]
	v_mov_b64_e32 v[34:35], v[2:3]
	v_mov_b64_e32 v[30:31], v[14:15]
	v_mov_b64_e32 v[28:29], v[12:13]
	v_mov_b64_e32 v[26:27], v[10:11]
	v_mov_b64_e32 v[24:25], v[8:9]
	v_mov_b64_e32 v[22:23], v[6:7]
	v_mov_b64_e32 v[20:21], v[4:5]
	v_mov_b64_e32 v[18:19], v[2:3]
	v_mov_b32_e32 v241, 0
	v_mov_b32_e32 v114, 0
	v_mov_b32_e32 v115, v240
	v_mov_b32_e32 v116, v240
	v_mov_b32_e32 v117, v240
	v_mov_b32_e32 v118, v240
	v_mov_b32_e32 v119, v240
	v_mov_b32_e32 v120, v240
	v_mov_b32_e32 v121, v240
	v_mov_b32_e32 v122, v240
	v_mov_b32_e32 v123, v240
	v_mov_b32_e32 v124, v240
	v_mov_b32_e32 v125, v240
	v_mov_b32_e32 v126, v240
	v_mov_b32_e32 v127, v240
	v_mov_b32_e32 v128, v240
	v_mov_b32_e32 v129, v240
.LBB0_56:
	s_andn2_b64 s[44:45], exec, s[82:83]
	s_add_u32 s16, s4, s86
	s_addc_u32 s17, s5, s87
	s_add_u32 s30, s6, s86
	s_addc_u32 s31, s7, s87
	s_andn2_b64 vcc, exec, s[82:83]
	s_cbranch_vccnz .LBB0_58
	s_add_i32 s15, s86, 0xc000
	s_and_b32 s15, s15, 0xc000
	s_add_i32 s40, s13, s15
	s_mov_b32 m0, s40
	s_add_i32 s15, s14, s15
	global_load_lds_dwordx4 v210, s[16:17]
	s_mov_b32 m0, s15
	s_nop 0
	global_load_lds_dwordx4 v208, s[30:31]
	s_add_i32 m0, s40, 0x400
	s_nop 0
	global_load_lds_dwordx4 v211, s[16:17]
	s_add_i32 m0, s15, 0x400
	s_nop 0
	global_load_lds_dwordx4 v209, s[30:31]

; #define PK4(P, BASE, OUT) do { unsigned a0 = cvtpk(P[BASE + 0], P[BASE + 1]), a1 = cvtpk(P[BASE + 2], P[BASE + 3]);   \
;     unsigned b0 = cvtpk(P[BASE + 4], P[BASE + 5]), b1 = cvtpk(P[BASE + 6], P[BASE + 7]);                              \
;     u32x4 w = {a0, a1, b0, b1}; OUT = *reinterpret_cast<bf16x8*>(&w); } while (0)
; #define PP_BAR(VM) do { if (VM) { asm volatile("s_waitcnt vmcnt(4) lgkmcnt(0)\n\ts_barrier" ::: "memory"); } else { asm volatile("s_waitcnt vmcnt(0) lgkmcnt(0)\n\ts_barrier" ::: "memory"); } } while (0)
; #define PP_BAR_PLAIN() asm volatile("s_waitcnt lgkmcnt(0)\n\ts_barrier" ::: "memory")
; __device__ __forceinline__ void finishSM(f32x16& p0, f32x16& p1, float alpha, float& l_reg, bf16x8& pa0, bf16x8& pa1, bf16x8& pa2, bf16x8& pa3) {
;   for (int r = 0; r < 16; ++r) p1[r] = __builtin_amdgcn_exp2f(p1[r]);
;   float ps = 0; for (int r = 0; r < 16; ++r) ps += p0[r]; for (int r = 0; r < 16; ++r) ps += p1[r];
;   { auto rr = __builtin_amdgcn_permlane32_swap(__float_as_uint(ps), __float_as_uint(ps), false, false);
;     ps = __uint_as_float(rr[0]) + __uint_as_float(rr[1]); }
;   l_reg = l_reg * alpha + ps;
;     ...
;   PK4(p0, 0, pa0); PK4(p0, 8, pa1); PK4(p1, 0, pa2); PK4(p1, 8, pa3);
;     ...
;       if (!(MK_PREB && t + 1 < NT)) { if (!grpB) PP_BAR(t + 2 < NT); else PP_BAR_PLAIN(); }
;       else if (!grpB) PP_BAR(t + 2 < NT);
;       if (!grpB && t + 3 < NT) DMA(t + 3, (t + 3) & 3);
.LBB0_65:
	v_exp_f32_e32 v98, v98
	v_exp_f32_e32 v99, v99
	v_exp_f32_e32 v100, v100
	v_exp_f32_e32 v101, v101
	v_exp_f32_e32 v102, v102
	v_add_f32_e32 v162, 0, v98
	v_exp_f32_e32 v103, v103
	v_add_f32_e32 v162, v99, v162
	v_exp_f32_e32 v104, v104
	v_add_f32_e32 v162, v100, v162
	v_exp_f32_e32 v105, v105
	v_add_f32_e32 v162, v101, v162
	v_exp_f32_e32 v106, v106
	v_add_f32_e32 v162, v102, v162
	v_exp_f32_e32 v107, v107
	v_add_f32_e32 v162, v103, v162
	v_exp_f32_e32 v108, v108
	v_add_f32_e32 v162, v104, v162
	v_exp_f32_e32 v109, v109
	v_add_f32_e32 v162, v105, v162
	v_exp_f32_e32 v110, v110
	v_add_f32_e32 v162, v106, v162
	v_exp_f32_e32 v111, v111
	v_add_f32_e32 v162, v107, v162
	v_exp_f32_e32 v112, v112
	v_add_f32_e32 v162, v108, v162
	v_exp_f32_e32 v113, v113
	v_add_f32_e32 v162, v109, v162
	v_exp_f32_e32 v82, v82
	v_add_f32_e32 v162, v110, v162
	v_exp_f32_e32 v83, v83
	v_add_f32_e32 v162, v111, v162
	v_exp_f32_e32 v84, v84
	v_add_f32_e32 v162, v112, v162
	v_exp_f32_e32 v85, v85
	v_add_f32_e32 v162, v113, v162
	v_exp_f32_e32 v86, v86
	v_add_f32_e32 v162, v82, v162
	v_exp_f32_e32 v87, v87
	v_add_f32_e32 v162, v83, v162
	v_exp_f32_e32 v88, v88
	v_add_f32_e32 v162, v84, v162
	v_exp_f32_e32 v89, v89
	v_add_f32_e32 v162, v85, v162
	v_exp_f32_e32 v90, v90
	v_add_f32_e32 v162, v86, v162
	v_exp_f32_e32 v91, v91
	v_add_f32_e32 v162, v87, v162
	v_exp_f32_e32 v92, v92
	v_add_f32_e32 v162, v88, v162
	v_exp_f32_e32 v93, v93
	v_add_f32_e32 v162, v89, v162
	v_exp_f32_e32 v94, v94
	v_add_f32_e32 v162, v90, v162
	v_exp_f32_e32 v95, v95
	v_add_f32_e32 v162, v91, v162
	v_exp_f32_e32 v96, v96
	v_add_f32_e32 v162, v92, v162
	v_exp_f32_e32 v97, v97
	v_add_f32_e32 v162, v93, v162
	v_add_f32_e32 v162, v94, v162
	v_add_f32_e32 v162, v95, v162
	v_add_f32_e32 v162, v96, v162
	v_add_f32_e32 v243, v97, v162
	v_mov_b32_e32 v245, v243
	v_cvt_pk_bf16_f32 v166, v82, v83
	s_nop 0
	v_permlane32_swap_b32_e32 v243, v245
	s_andn2_b64 s[42:43], exec, s[0:1]
	s_andn2_b64 vcc, exec, s[0:1]
	v_cvt_pk_bf16_f32 v174, v98, v99
	v_cvt_pk_bf16_f32 v175, v100, v101
	v_cvt_pk_bf16_f32 v176, v102, v103
	v_cvt_pk_bf16_f32 v177, v104, v105
	v_cvt_pk_bf16_f32 v170, v106, v107
	v_cvt_pk_bf16_f32 v171, v108, v109
	v_cvt_pk_bf16_f32 v172, v110, v111
	v_cvt_pk_bf16_f32 v173, v112, v113
	v_cvt_pk_bf16_f32 v167, v84, v85
	v_cvt_pk_bf16_f32 v168, v86, v87
	v_cvt_pk_bf16_f32 v169, v88, v89
	v_cvt_pk_bf16_f32 v162, v90, v91
	v_cvt_pk_bf16_f32 v163, v92, v93
	v_cvt_pk_bf16_f32 v164, v94, v95
	v_cvt_pk_bf16_f32 v165, v96, v97
	s_cbranch_vccnz .LBB0_67
	s_add_i32 s15, s86, 0xc000
	s_and_b32 s15, s15, 0xc000
	s_add_i32 s84, s13, s15
	s_waitcnt vmcnt(4) lgkmcnt(0)
	s_barrier
	s_mov_b32 m0, s84
	s_add_i32 s15, s14, s15
	global_load_lds_dwordx4 v210, s[16:17]
	s_mov_b32 m0, s15
	s_nop 0
	global_load_lds_dwordx4 v208, s[30:31]
	s_add_i32 m0, s84, 0x400
	s_nop 0
	global_load_lds_dwordx4 v211, s[16:17]
	s_add_i32 m0, s15, 0x400
	s_nop 0
	global_load_lds_dwordx4 v209, s[30:31]
